# adds: gla3 previous-state loads issued at item start
# speedup vs baseline: 1.0059x; 1.0042x over previous
; __device__ __forceinline__ size_t pidx(int row, int col) { return (size_t)(col >> 7) * ((size_t)T * 128) + (size_t)row * 128 + (col & 127); }
; __device__ __forceinline__ void gla3_item(const Params& p, int item, int l, unsigned char* lds) {
;     ...
;     const int h = item >> 7, n = item & 127, t0 = 64 * n;
;     float* cum = (float*)lds; bf16_t* ST = (bf16_t*)lds;
;     bf16_t* Qp = (bf16_t*)(lds + 69632); bf16_t* Kp = (bf16_t*)(lds + 87040); bf16_t* VT = (bf16_t*)(lds + 104448);
;     float* c31 = (float*)(lds + 141312); float* ssq = (float*)(lds + 141824);
;     __syncthreads();
; #pragma unroll
;     for (int i = 0; i < 4; ++i) { const int idx = tid + 512 * i, c = idx >> 5, d4 = idx & 31; *(f32x4*)(cum + c * 128 + d4 * 4) = *(const f32x4*)(cumg + (size_t)(t0 + c) * 512 + h * 128 + d4 * 4); }
;     u32x4 rq[2], rk[2];
; #pragma unroll
;     for (int i = 0; i < 2; ++i) {
;         const int idx = tid + 512 * i, c = idx >> 4, ch = idx & 15;
;         rq[i] = *(const u32x4*)(P + pidx(t0 + c, C_QG + h * 128 + ch * 8));
;         rk[i] = *(const u32x4*)(P + pidx(t0 + c, C_KG + h * 128 + ch * 8));
;     }
;     stage_vt<64>(VT, 72, P, t0, 1, C_VG + h * 256, 32);
;     __syncthreads();
;     const bf16_t* sp = (const bf16_t*)(p.ws + W_SP) + (size_t)(h * 128 + n) * 32768;
;     u32x4 sv[8];
; #pragma unroll
;     for (int i = 0; i < 8; ++i) { const int idx = tid + 512 * i, e = idx >> 4, ch = idx & 15; sv[i] = *(const u32x4*)(sp + e * 128 + ch * 8); }
.LBB0_57:
	s_lshl_b32 s4, s38, 6
	s_and_b32 s13, s4, 0x1fc0
	s_and_b32 s4, s38, 0xffffff80
	v_mov_b32_e32 v60, v185
	s_ashr_i32 s5, s4, 31
	s_lshl_b64 s[4:5], s[4:5], 2
	s_waitcnt vmcnt(0)
	v_ashrrev_i32_e32 v9, 5, v60
	s_add_u32 s4, s7, s4
	v_lshlrev_b32_e32 v0, 4, v60
	v_add_u32_e32 v2, s13, v9
	s_addc_u32 s5, s8, s5
	v_and_b32_e32 v0, 0x1f0, v0
	v_ashrrev_i32_e32 v3, 31, v2
	v_lshl_add_u64 v[6:7], s[4:5], 0, v[0:1]
	v_lshlrev_b64 v[2:3], 11, v[2:3]
	v_lshl_add_u64 v[2:3], v[6:7], 0, v[2:3]
	s_waitcnt lgkmcnt(0)
	s_barrier
	v_mov_b64_e32 v[88:89], v[2:3]
	s_mov_b64 s[4:5], 0x8000
	flat_load_dwordx4 v[2:5], v[2:3]
	v_lshl_add_u64 v[90:91], v[88:89], 0, s[4:5]
	flat_load_dwordx4 v[92:95], v[90:91]
	v_lshl_add_u64 v[90:91], v[90:91], 0, s[4:5]
	flat_load_dwordx4 v[96:99], v[90:91]
	v_lshl_add_u64 v[90:91], v[90:91], 0, s[4:5]
	flat_load_dwordx4 v[100:103], v[90:91]
	v_add_u32_e32 v10, 0x200, v60
	v_ashrrev_i32_e32 v11, 5, v10
	v_add_u32_e32 v0, 0, v0
	v_add_u32_e32 v8, s13, v11
	v_lshl_add_u32 v12, v9, 9, v0
	v_ashrrev_i32_e32 v9, 31, v8
	v_lshlrev_b64 v[8:9], 11, v[8:9]
	v_lshl_add_u64 v[8:9], v[6:7], 0, v[8:9]
	v_add_u32_e32 v63, 0x400, v60
	v_lshl_add_u32 v11, v11, 9, v0
	v_add_u32_e32 v62, 0x600, v60
	s_add_i32 s4, s38, 0x1200
	s_ashr_i32 s4, s4, 7
	s_ashr_i32 s5, s4, 31
	s_lshl_b64 s[4:5], s[4:5], 21
	s_add_u32 s4, s0, s4
	v_mov_b32_e32 v51, v1
	s_addc_u32 s5, s1, s5
	s_add_i32 s15, s38, 0x1400
	v_ashrrev_i32_e32 v59, 4, v60
	v_ashrrev_i32_e32 v64, 4, v10
	v_add_u32_e32 v10, s13, v64
	s_waitcnt vmcnt(0) lgkmcnt(0)
	ds_write_b128 v12, v[2:5]
	v_ashrrev_i32_e32 v12, 5, v63
	v_add_u32_e32 v8, s13, v12
	v_ashrrev_i32_e32 v9, 31, v8
	v_lshlrev_b64 v[8:9], 11, v[8:9]
	v_lshl_add_u64 v[8:9], v[6:7], 0, v[8:9]
	v_lshl_add_u32 v12, v12, 9, v0
	ds_write_b128 v11, v[92:95]
	v_ashrrev_i32_e32 v11, 5, v62
	v_add_u32_e32 v8, s13, v11
	v_ashrrev_i32_e32 v9, 31, v8
	v_lshlrev_b64 v[8:9], 11, v[8:9]
	v_lshl_add_u64 v[6:7], v[6:7], 0, v[8:9]
	v_add_u32_e32 v8, s13, v59
	v_ashrrev_i32_e32 v9, 31, v8
	v_lshl_add_u32 v0, v11, 9, v0
	v_lshlrev_b64 v[8:9], 8, v[8:9]
	v_ashrrev_i32_e32 v11, 31, v10
	v_lshlrev_b64 v[10:11], 8, v[10:11]
	ds_write_b128 v12, v[96:99]
	v_lshlrev_b32_e32 v2, 3, v60
	v_and_b32_e32 v52, 0x78, v2
	v_lshlrev_b32_e32 v50, 1, v52
	s_mov_b32 s44, s38
	s_ashr_i32 s45, s38, 31
	s_lshl_b64 s[44:45], s[44:45], 16
	s_add_u32 s44, s10, s44
	s_addc_u32 s45, s11, s45
	v_mov_b32_e32 v228, v50
	v_mov_b32_e32 v229, 0
	v_lshl_add_u64 v[228:229], s[44:45], 0, v[228:229]
	v_and_b32_e32 v230, 0xffffff80, v2
	v_mov_b32_e32 v232, v230
	v_ashrrev_i32_e32 v233, 31, v232
	v_lshl_add_u64 v[232:233], v[232:233], 1, v[228:229]
	global_load_dwordx4 v[186:189], v[232:233], off
	v_add_u32_e32 v232, 0x1000, v230
	v_ashrrev_i32_e32 v233, 31, v232
	v_lshl_add_u64 v[232:233], v[232:233], 1, v[228:229]
	global_load_dwordx4 v[190:193], v[232:233], off
	v_add_u32_e32 v232, 0x2000, v230
	v_ashrrev_i32_e32 v233, 31, v232
	v_lshl_add_u64 v[232:233], v[232:233], 1, v[228:229]
	global_load_dwordx4 v[194:197], v[232:233], off
	v_add_u32_e32 v232, 0x3000, v230
	v_ashrrev_i32_e32 v233, 31, v232
	v_lshl_add_u64 v[232:233], v[232:233], 1, v[228:229]
	global_load_dwordx4 v[198:201], v[232:233], off
	v_add_u32_e32 v232, 0x4000, v230
	v_ashrrev_i32_e32 v233, 31, v232
	v_lshl_add_u64 v[232:233], v[232:233], 1, v[228:229]
	global_load_dwordx4 v[202:205], v[232:233], off
	v_add_u32_e32 v232, 0x5000, v230
	v_ashrrev_i32_e32 v233, 31, v232
	v_lshl_add_u64 v[232:233], v[232:233], 1, v[228:229]
	global_load_dwordx4 v[206:209], v[232:233], off
	v_add_u32_e32 v232, 0x6000, v230
	v_ashrrev_i32_e32 v233, 31, v232
	v_lshl_add_u64 v[232:233], v[232:233], 1, v[228:229]
	global_load_dwordx4 v[220:223], v[232:233], off
	v_add_u32_e32 v232, 0x7000, v230
	v_ashrrev_i32_e32 v233, 31, v232
	v_lshl_add_u64 v[232:233], v[232:233], 1, v[228:229]
	global_load_dwordx4 v[224:227], v[232:233], off
	v_lshl_add_u64 v[12:13], s[4:5], 0, v[50:51]
	s_ashr_i32 s4, s15, 7
	s_ashr_i32 s5, s4, 31
	s_lshl_b64 s[4:5], s[4:5], 21
	s_add_u32 s4, s0, s4
	s_addc_u32 s5, s1, s5
	v_lshl_add_u64 v[14:15], v[12:13], 0, v[8:9]
	v_lshl_add_u64 v[16:17], s[4:5], 0, v[50:51]
	v_lshl_add_u64 v[12:13], v[12:13], 0, v[10:11]
	v_lshl_add_u64 v[8:9], v[16:17], 0, v[8:9]
	v_lshl_add_u64 v[10:11], v[16:17], 0, v[10:11]
	s_lshl_b32 s4, s38, 1
	v_mov_b32_e32 v3, v185
	s_and_b32 s40, s4, 0xffffff00
	ds_write_b128 v0, v[100:103]
	flat_load_dwordx4 v[46:49], v[14:15]
	flat_load_dwordx4 v[42:45], v[8:9]
	flat_load_dwordx4 v[26:29], v[12:13]
	flat_load_dwordx4 v[22:25], v[10:11]
	s_nop 0
	v_cmp_gt_i32_e32 vcc, s33, v3
	s_and_saveexec_b64 s[42:43], vcc
	s_cbranch_execz .LBB0_60
; __device__ __forceinline__ int tidx() { int t = threadIdx.x; asm volatile("" : "+v"(t)); return t; }
; __device__ __forceinline__ size_t pidx(int row, int col) { return (size_t)(col >> 7) * ((size_t)T * 128) + (size_t)row * 128 + (col & 127); }
; template <int nkeys> __device__ __forceinline__ void stage_vt(bf16_t* VT, int pitch, const bf16_t* P, int r0, int rstride, int col, int nch) {
;     const int tid = tidx();
;     for (int idx = tid; idx < nkeys * nch; idx += 512) {
;         const int key = idx % nkeys, ch = idx / nkeys;
;         const u32x4 raw = *(const u32x4*)(P + pidx(r0 + key * rstride, col + ch * 8));
;         bf16_t* d = VT + (ch * 8) * pitch + key;
;         d[0] = (bf16_t)(raw[0] & 0xffff); d[pitch] = (bf16_t)(raw[0] >> 16); d[2 * pitch] = (bf16_t)(raw[1] & 0xffff); d[3 * pitch] = (bf16_t)(raw[1] >> 16);
;         d[4 * pitch] = (bf16_t)(raw[2] & 0xffff); d[5 * pitch] = (bf16_t)(raw[2] >> 16); d[6 * pitch] = (bf16_t)(raw[3] & 0xffff); d[7 * pitch] = (bf16_t)(raw[3] >> 16);
;     }
; }
	v_readlane_b32 s15, v246, 53
	s_and_b32 s4, s12, 0x1fc0
	s_add_i32 s5, s40, 0x1600
	v_lshl_add_u32 v4, v3, 1, s15
	v_mov_b32_e32 v137, 0
	v_ashrrev_i32_e32 v136, 31, v3
	v_lshrrev_b32_e32 v136, 26, v136
	v_add_u32_e32 v136, v3, v136
	v_add_u32_e32 v138, s4, v3
	v_ashrrev_i32_e32 v144, 6, v136
	v_and_b32_e32 v136, 0xffffffc0, v136
	v_sub_u32_e32 v140, v138, v136
	v_lshl_add_u32 v136, v144, 3, s5
	v_ashrrev_i32_e32 v142, 7, v136
	v_ashrrev_i32_e32 v143, 31, v142
	v_ashrrev_i32_e32 v141, 31, v140
	v_lshlrev_b64 v[142:143], 21, v[142:143]
	v_lshlrev_b32_e32 v138, 4, v144
	v_lshlrev_b64 v[140:141], 8, v[140:141]
	v_lshl_add_u64 v[142:143], s[0:1], 0, v[142:143]
	v_and_b32_e32 v136, 0xf0, v138
	v_lshl_add_u64 v[140:141], v[142:143], 0, v[140:141]
	v_lshl_add_u64 v[140:141], v[140:141], 0, v[136:137]
	flat_load_dwordx4 v[120:123], v[140:141]
	v_lshl_add_u32 v145, v144, 10, v4
	v_add_u32_e32 v158, 0x200, v3
	v_mov_b32_e32 v149, 0
	v_ashrrev_i32_e32 v148, 31, v158
	v_lshrrev_b32_e32 v148, 26, v148
	v_add_u32_e32 v148, v158, v148
	v_add_u32_e32 v150, s4, v158
	v_ashrrev_i32_e32 v156, 6, v148
	v_and_b32_e32 v148, 0xffffffc0, v148
	v_sub_u32_e32 v152, v150, v148
	v_lshl_add_u32 v148, v156, 3, s5
	v_ashrrev_i32_e32 v154, 7, v148
	v_ashrrev_i32_e32 v155, 31, v154
	v_ashrrev_i32_e32 v153, 31, v152
	v_lshlrev_b64 v[154:155], 21, v[154:155]
	v_lshlrev_b32_e32 v150, 4, v156
	v_lshlrev_b64 v[152:153], 8, v[152:153]
	v_lshl_add_u64 v[154:155], s[0:1], 0, v[154:155]
	v_and_b32_e32 v148, 0xf0, v150
	v_lshl_add_u64 v[152:153], v[154:155], 0, v[152:153]
	v_lshl_add_u64 v[152:153], v[152:153], 0, v[148:149]
	flat_load_dwordx4 v[124:127], v[152:153]
	v_add_u32_e32 v157, 0x400, v4
	v_lshl_add_u32 v157, v156, 10, v157
	v_add_u32_e32 v170, 0x400, v3
	v_mov_b32_e32 v161, 0
	v_ashrrev_i32_e32 v160, 31, v170
	v_lshrrev_b32_e32 v160, 26, v160
	v_add_u32_e32 v160, v170, v160
	v_add_u32_e32 v162, s4, v170
	v_ashrrev_i32_e32 v168, 6, v160
	v_and_b32_e32 v160, 0xffffffc0, v160
	v_sub_u32_e32 v164, v162, v160
	v_lshl_add_u32 v160, v168, 3, s5
	v_ashrrev_i32_e32 v166, 7, v160
	v_ashrrev_i32_e32 v167, 31, v166
	v_ashrrev_i32_e32 v165, 31, v164
	v_lshlrev_b64 v[166:167], 21, v[166:167]
	v_lshlrev_b32_e32 v162, 4, v168
	v_lshlrev_b64 v[164:165], 8, v[164:165]
	v_lshl_add_u64 v[166:167], s[0:1], 0, v[166:167]
	v_and_b32_e32 v160, 0xf0, v162
	v_lshl_add_u64 v[164:165], v[166:167], 0, v[164:165]
	v_lshl_add_u64 v[164:165], v[164:165], 0, v[160:161]
	flat_load_dwordx4 v[128:131], v[164:165]
	v_add_u32_e32 v169, 0x800, v4
	v_lshl_add_u32 v169, v168, 10, v169
	v_add_u32_e32 v182, 0x600, v3
	v_mov_b32_e32 v173, 0
	v_ashrrev_i32_e32 v172, 31, v182
	v_lshrrev_b32_e32 v172, 26, v172
	v_add_u32_e32 v172, v182, v172
	v_add_u32_e32 v174, s4, v182
	v_ashrrev_i32_e32 v180, 6, v172
	v_and_b32_e32 v172, 0xffffffc0, v172
	v_sub_u32_e32 v176, v174, v172
	v_lshl_add_u32 v172, v180, 3, s5
	v_ashrrev_i32_e32 v178, 7, v172
	v_ashrrev_i32_e32 v179, 31, v178
	v_ashrrev_i32_e32 v177, 31, v176
	v_lshlrev_b64 v[178:179], 21, v[178:179]
	v_lshlrev_b32_e32 v174, 4, v180
	v_lshlrev_b64 v[176:177], 8, v[176:177]
	v_lshl_add_u64 v[178:179], s[0:1], 0, v[178:179]
	v_and_b32_e32 v172, 0xf0, v174
	v_lshl_add_u64 v[176:177], v[178:179], 0, v[176:177]
	v_lshl_add_u64 v[176:177], v[176:177], 0, v[172:173]
	flat_load_dwordx4 v[132:135], v[176:177]
	v_add_u32_e32 v181, 0xc00, v4
	v_lshl_add_u32 v181, v180, 10, v181
	s_waitcnt vmcnt(0) lgkmcnt(0)
	ds_write_b16 v145, v120
	ds_write_b16_d16_hi v145, v120 offset:144
	ds_write_b16 v145, v121 offset:288
	ds_write_b16_d16_hi v145, v121 offset:432
	ds_write_b16 v145, v122 offset:576
	ds_write_b16_d16_hi v145, v122 offset:720
	ds_write_b16 v145, v123 offset:864
	ds_write_b16_d16_hi v145, v123 offset:1008
	ds_write_b16 v157, v124
	ds_write_b16_d16_hi v157, v124 offset:144
	ds_write_b16 v157, v125 offset:288
	ds_write_b16_d16_hi v157, v125 offset:432
	ds_write_b16 v157, v126 offset:576
	ds_write_b16_d16_hi v157, v126 offset:720
	ds_write_b16 v157, v127 offset:864
	ds_write_b16_d16_hi v157, v127 offset:1008
	ds_write_b16 v169, v128
	ds_write_b16_d16_hi v169, v128 offset:144
	ds_write_b16 v169, v129 offset:288
	ds_write_b16_d16_hi v169, v129 offset:432
	ds_write_b16 v169, v130 offset:576
	ds_write_b16_d16_hi v169, v130 offset:720
	ds_write_b16 v169, v131 offset:864
	ds_write_b16_d16_hi v169, v131 offset:1008
	ds_write_b16 v181, v132
	ds_write_b16_d16_hi v181, v132 offset:144
	ds_write_b16 v181, v133 offset:288
	ds_write_b16_d16_hi v181, v133 offset:432
	ds_write_b16 v181, v134 offset:576
	ds_write_b16_d16_hi v181, v134 offset:720
	ds_write_b16 v181, v135 offset:864
	ds_write_b16_d16_hi v181, v135 offset:1008
; __device__ __forceinline__ unsigned pk2(float lo, float hi) { const f32v2_t v = {lo, hi}; return __builtin_bit_cast(unsigned, __builtin_convertvector(v, bf16v2_t)); }
; __device__ __forceinline__ float bflo(unsigned u) { return __uint_as_float(u << 16); }
; __device__ __forceinline__ float bfhi(unsigned u) { return __uint_as_float(u & 0xffff0000u); }
; __device__ __forceinline__ void gla3_item(const Params& p, int item, int l, unsigned char* lds) {
;     ...
;     float f31[8];
;     {
;         const int ch = tid & 15;
; #pragma unroll
;         for (int j = 0; j < 8; ++j) f31[j] = __expf(cum[31 * 128 + ch * 8 + j]);
;     }
; #pragma unroll
;     for (int i = 0; i < 2; ++i) {
;         const int idx = tid + 512 * i, c = idx >> 4, ch = idx & 15;
;         const float qv[8] = {bflo(rq[i][0]), bfhi(rq[i][0]), bflo(rq[i][1]), bfhi(rq[i][1]), bflo(rq[i][2]), bfhi(rq[i][2]), bflo(rq[i][3]), bfhi(rq[i][3])};
;         const float kv[8] = {bflo(rk[i][0]), bfhi(rk[i][0]), bflo(rk[i][1]), bfhi(rk[i][1]), bflo(rk[i][2]), bfhi(rk[i][2]), bflo(rk[i][3]), bfhi(rk[i][3])};
;         float qo[8], ko[8];
; #pragma unroll
;         for (int e = 0; e < 8; ++e) {
;             const int d = ch * 8 + e;
;             const float df = cum[c * 128 + d] - cum[31 * 128 + d];
;             qo[e] = qv[e] * 0.08838834764831845f * __expf(df); ko[e] = kv[e] * __expf(-df);
;         }
;         u32x4 oq = {pk2(qo[0], qo[1]), pk2(qo[2], qo[3]), pk2(qo[4], qo[5]), pk2(qo[6], qo[7])};
;         u32x4 ok = {pk2(ko[0], ko[1]), pk2(ko[2], ko[3]), pk2(ko[4], ko[5]), pk2(ko[6], ko[7])};
;         *(u32x4*)(Qp + c * 136 + ch * 8) = oq; *(u32x4*)(Kp + c * 136 + ch * 8) = ok;
.LBB0_60:
	s_or_b64 exec, exec, s[42:43]
	s_ashr_i32 s39, s38, 31
	s_lshl_b64 s[4:5], s[38:39], 16
	s_add_u32 s4, s10, s4
	s_addc_u32 s5, s11, s5
	v_mov_b32_e32 v51, v1
	v_and_b32_e32 v2, 0xffffff80, v2
	v_lshl_add_u64 v[4:5], s[4:5], 0, v[50:51]
	v_ashrrev_i32_e32 v3, 31, v2
	v_add_u32_e32 v8, 0x1000, v2
	v_lshl_add_u64 v[6:7], v[2:3], 1, v[4:5]
	v_ashrrev_i32_e32 v9, 31, v8
	s_waitcnt lgkmcnt(0)
	s_barrier
	v_lshl_add_u64 v[8:9], v[8:9], 1, v[4:5]
	v_mov_b64_e32 v[38:39], v[186:187]
	v_mov_b64_e32 v[40:41], v[188:189]
	v_mov_b64_e32 v[34:35], v[190:191]
	v_mov_b64_e32 v[36:37], v[192:193]
	v_add_u32_e32 v6, 0x2000, v2
	v_ashrrev_i32_e32 v7, 31, v6
	v_add_u32_e32 v8, 0x3000, v2
	v_lshl_add_u64 v[6:7], v[6:7], 1, v[4:5]
	v_ashrrev_i32_e32 v9, 31, v8
	v_lshl_add_u64 v[8:9], v[8:9], 1, v[4:5]
	v_mov_b64_e32 v[30:31], v[194:195]
	v_mov_b64_e32 v[32:33], v[196:197]
	v_mov_b64_e32 v[18:19], v[198:199]
	v_mov_b64_e32 v[20:21], v[200:201]
	v_add_u32_e32 v6, 0x4000, v2
	v_ashrrev_i32_e32 v7, 31, v6
	v_add_u32_e32 v8, 0x5000, v2
	v_lshl_add_u64 v[6:7], v[6:7], 1, v[4:5]
	v_ashrrev_i32_e32 v9, 31, v8
	v_lshl_add_u64 v[8:9], v[8:9], 1, v[4:5]
	v_mov_b64_e32 v[14:15], v[202:203]
	v_mov_b64_e32 v[16:17], v[204:205]
	v_mov_b64_e32 v[10:11], v[206:207]
	v_mov_b64_e32 v[12:13], v[208:209]
	v_add_u32_e32 v6, 0x6000, v2
	v_add_u32_e32 v2, 0x7000, v2
	v_and_b32_e32 v61, 15, v60
	v_ashrrev_i32_e32 v7, 31, v6
	v_ashrrev_i32_e32 v3, 31, v2
	v_lshl_add_u64 v[6:7], v[6:7], 1, v[4:5]
	v_lshl_add_u64 v[2:3], v[2:3], 1, v[4:5]
	v_lshl_add_u32 v0, v52, 2, 0
	v_lshl_add_u32 v51, v61, 5, 0
	v_mov_b64_e32 v[6:7], v[220:221]
	v_mov_b64_e32 v[8:9], v[222:223]
	s_nop 0
	v_mov_b64_e32 v[2:3], v[224:225]
	v_mov_b64_e32 v[4:5], v[226:227]
	ds_read_b32 v0, v0 offset:15872
	v_add_u32_e32 v52, 0x3800, v51
	ds_read2_b64 v[66:69], v52 offset0:192 offset1:193
	v_add_u32_e32 v53, 0x3e04, v51
	v_add_u32_e32 v54, 0x3e0c, v51
	ds_read_b32 v65, v51 offset:15900
	ds_read2_b32 v[82:83], v53 offset1:1
	ds_read2_b32 v[84:85], v54 offset1:1
	s_waitcnt lgkmcnt(0)
	v_mul_f32_e32 v0, 0x3fb8aa3b, v0
	v_exp_f32_e32 v56, v0
	ds_read2_b64 v[70:73], v52 offset0:194 offset1:195
	v_mul_f32_e32 v0, 0x3fb8aa3b, v67
	v_exp_f32_e32 v57, v0
	v_mul_f32_e32 v0, 0x3fb8aa3b, v83
	v_exp_f32_e32 v54, v0
	v_mul_f32_e32 v0, 0x3fb8aa3b, v69
	v_exp_f32_e32 v55, v0
	v_mul_f32_e32 v0, 0x3fb8aa3b, v85
	v_exp_f32_e32 v52, v0
	v_add_u32_e32 v0, 0x3e14, v51
	ds_read2_b32 v[86:87], v0 offset1:1
	s_waitcnt lgkmcnt(0)
	v_mul_f32_e32 v0, 0x3fb8aa3b, v71
	v_exp_f32_e32 v53, v0
	v_lshl_add_u32 v0, v59, 9, v51
	ds_read_b128 v[74:77], v0
	ds_read_b128 v[78:81], v0 offset:16
	v_lshlrev_b32_e32 v67, 4, v61
	v_readlane_b32 s15, v246, 54
	v_readlane_b32 s16, v246, 55
	s_waitcnt lgkmcnt(0)
	v_sub_f32_e32 v0, v74, v66
	v_mul_f32_e32 v66, 0x3fb8aa3b, v0
	v_mul_f32_e32 v0, 0xbfb8aa3b, v0
	v_exp_f32_e32 v74, v0
	v_sub_f32_e32 v0, v75, v82
	v_mul_f32_e32 v58, 0x3fb8aa3b, v87
	v_add_u32_e32 v85, s15, v67
	v_add_u32_e32 v87, s16, v67
	v_mul_f32_e32 v67, 0x3fb8aa3b, v0
	v_exp_f32_e32 v66, v66
	v_exp_f32_e32 v67, v67
	s_waitcnt vmcnt(0)
	v_lshlrev_b32_e32 v82, 16, v46
	v_and_b32_e32 v83, 0xffff0000, v46
	s_mov_b32 s4, 0x3db504f3
	v_mul_f32_e32 v0, 0xbfb8aa3b, v0
	v_pk_mul_f32 v[82:83], v[82:83], s[4:5] op_sel_hi:[1,0]
	v_exp_f32_e32 v75, v0
	v_sub_f32_e32 v0, v76, v68
	v_pk_mul_f32 v[66:67], v[82:83], v[66:67]
	v_lshlrev_b32_e32 v82, 16, v42
	v_and_b32_e32 v83, 0xffff0000, v42
	v_mul_f32_e32 v42, 0x3fb8aa3b, v0
	v_mul_f32_e32 v0, 0xbfb8aa3b, v0
	v_exp_f32_e32 v46, v0
	v_sub_f32_e32 v0, v77, v84
	v_exp_f32_e32 v68, v42
	v_mul_f32_e32 v42, 0x3fb8aa3b, v0
	v_mul_f32_e32 v0, 0xbfb8aa3b, v0
	v_exp_f32_e32 v69, v42
	v_lshlrev_b32_e32 v76, 16, v47
	v_and_b32_e32 v77, 0xffff0000, v47
	v_exp_f32_e32 v47, v0
	v_pk_mul_f32 v[76:77], v[76:77], s[4:5] op_sel_hi:[1,0]
	v_lshlrev_b32_e32 v42, 16, v43
	v_and_b32_e32 v43, 0xffff0000, v43
	v_sub_f32_e32 v0, v78, v70
	v_pk_mul_f32 v[68:69], v[76:77], v[68:69]
	v_pk_mul_f32 v[76:77], v[46:47], v[42:43]
	v_mul_f32_e32 v42, 0x3fb8aa3b, v0
	v_mul_f32_e32 v0, 0xbfb8aa3b, v0
	v_exp_f32_e32 v46, v0
	v_sub_f32_e32 v0, v79, v86
	v_mul_f32_e32 v43, 0x3fb8aa3b, v0
	v_exp_f32_e32 v42, v42
	v_exp_f32_e32 v43, v43
	v_mul_f32_e32 v0, 0xbfb8aa3b, v0
	v_exp_f32_e32 v47, v0
	v_lshlrev_b32_e32 v70, 16, v48
	v_and_b32_e32 v71, 0xffff0000, v48
	v_pk_mul_f32 v[70:71], v[70:71], s[4:5] op_sel_hi:[1,0]
	v_sub_f32_e32 v0, v80, v72
	v_pk_mul_f32 v[70:71], v[70:71], v[42:43]
	v_lshlrev_b32_e32 v42, 16, v44
	v_and_b32_e32 v43, 0xffff0000, v44
	v_pk_mul_f32 v[78:79], v[46:47], v[42:43]
	v_mul_f32_e32 v42, 0x3fb8aa3b, v0
	v_mul_f32_e32 v0, 0xbfb8aa3b, v0
	v_exp_f32_e32 v46, v0
	v_sub_f32_e32 v0, v81, v65
	v_mul_f32_e32 v43, 0x3fb8aa3b, v0
	v_exp_f32_e32 v42, v42
	v_exp_f32_e32 v43, v43
	v_mul_f32_e32 v0, 0xbfb8aa3b, v0
	v_exp_f32_e32 v47, v0
	v_lshlrev_b32_e32 v48, 16, v49
	v_and_b32_e32 v49, 0xffff0000, v49
	v_pk_mul_f32 v[48:49], v[48:49], s[4:5] op_sel_hi:[1,0]
	s_movk_i32 s17, 0x110
	v_pk_mul_f32 v[48:49], v[48:49], v[42:43]
	v_lshlrev_b32_e32 v42, 16, v45
	v_and_b32_e32 v43, 0xffff0000, v45
	v_mul_lo_u32 v65, v59, s17
	v_pk_mul_f32 v[74:75], v[74:75], v[82:83]
	v_pk_mul_f32 v[80:81], v[46:47], v[42:43]
	v_cvt_pk_bf16_f32 v42, v66, v67
	v_cvt_pk_bf16_f32 v43, v68, v69
	v_cvt_pk_bf16_f32 v44, v70, v71
	v_cvt_pk_bf16_f32 v45, v48, v49
	v_add_u32_e32 v0, v85, v65
	v_cvt_pk_bf16_f32 v46, v74, v75
	v_cvt_pk_bf16_f32 v47, v76, v77
	v_cvt_pk_bf16_f32 v48, v78, v79
	v_cvt_pk_bf16_f32 v49, v80, v81
	ds_write_b128 v0, v[42:45]
	v_add_u32_e32 v0, v87, v65
	ds_write_b128 v0, v[46:49]
	v_lshl_add_u32 v0, v64, 9, v51
	ds_read_b128 v[42:45], v0
	ds_read_b128 v[46:49], v51 offset:15872
	v_mul_f32_e32 v59, 0x3fb8aa3b, v73
	ds_read_b128 v[66:69], v0 offset:16
	ds_read_b128 v[70:73], v51 offset:15888
	v_lshlrev_b32_e32 v74, 16, v26
	v_and_b32_e32 v75, 0xffff0000, v26
	s_waitcnt lgkmcnt(2)
; __device__ __forceinline__ unsigned pk2(float lo, float hi) { const f32v2_t v = {lo, hi}; return __builtin_bit_cast(unsigned, __builtin_convertvector(v, bf16v2_t)); }
; __device__ __forceinline__ float bflo(unsigned u) { return __uint_as_float(u << 16); }
; __device__ __forceinline__ float bfhi(unsigned u) { return __uint_as_float(u & 0xffff0000u); }
; __device__ __forceinline__ void gla3_item(const Params& p, int item, int l, unsigned char* lds) {
;     ...
; #pragma unroll
;     for (int i = 0; i < 2; ++i) {
;         const int idx = tid + 512 * i, c = idx >> 4, ch = idx & 15;
;         const float qv[8] = {bflo(rq[i][0]), bfhi(rq[i][0]), bflo(rq[i][1]), bfhi(rq[i][1]), bflo(rq[i][2]), bfhi(rq[i][2]), bflo(rq[i][3]), bfhi(rq[i][3])};
;         const float kv[8] = {bflo(rk[i][0]), bfhi(rk[i][0]), bflo(rk[i][1]), bfhi(rk[i][1]), bflo(rk[i][2]), bfhi(rk[i][2]), bflo(rk[i][3]), bfhi(rk[i][3])};
;         float qo[8], ko[8];
; #pragma unroll
;         for (int e = 0; e < 8; ++e) {
;             const int d = ch * 8 + e;
;             const float df = cum[c * 128 + d] - cum[31 * 128 + d];
;             qo[e] = qv[e] * 0.08838834764831845f * __expf(df); ko[e] = kv[e] * __expf(-df);
;         }
;         u32x4 oq = {pk2(qo[0], qo[1]), pk2(qo[2], qo[3]), pk2(qo[4], qo[5]), pk2(qo[6], qo[7])};
;         u32x4 ok = {pk2(ko[0], ko[1]), pk2(ko[2], ko[3]), pk2(ko[4], ko[5]), pk2(ko[6], ko[7])};
;         *(u32x4*)(Qp + c * 136 + ch * 8) = oq; *(u32x4*)(Kp + c * 136 + ch * 8) = ok;
;     }
;     __syncthreads();
; #pragma unroll
;     for (int i = 0; i < 8; ++i) {
;         const int idx = tid + 512 * i, e = idx >> 4, ch = idx & 15;
;         u32x4 o = {pk2(bflo(sv[i][0]) * f31[0], bfhi(sv[i][0]) * f31[1]), pk2(bflo(sv[i][1]) * f31[2], bfhi(sv[i][1]) * f31[3]),
;                    pk2(bflo(sv[i][2]) * f31[4], bfhi(sv[i][2]) * f31[5]), pk2(bflo(sv[i][3]) * f31[6], bfhi(sv[i][3]) * f31[7])};
;         *(u32x4*)(ST + e * 136 + ch * 8) = o;
;     }
;     __syncthreads();
	v_sub_f32_e32 v0, v42, v46
	v_mul_f32_e32 v42, 0x3fb8aa3b, v0
	v_mul_f32_e32 v0, 0xbfb8aa3b, v0
	v_exp_f32_e32 v46, v0
	v_sub_f32_e32 v0, v43, v47
	v_mul_f32_e32 v43, 0x3fb8aa3b, v0
	v_exp_f32_e32 v42, v42
	v_exp_f32_e32 v43, v43
	v_mul_f32_e32 v0, 0xbfb8aa3b, v0
	v_pk_mul_f32 v[74:75], v[74:75], s[4:5] op_sel_hi:[1,0]
	v_exp_f32_e32 v47, v0
	v_sub_f32_e32 v0, v44, v48
	v_pk_mul_f32 v[42:43], v[74:75], v[42:43]
	v_lshlrev_b32_e32 v74, 16, v22
	v_and_b32_e32 v75, 0xffff0000, v22
	v_mul_f32_e32 v22, 0x3fb8aa3b, v0
	v_mul_f32_e32 v0, 0xbfb8aa3b, v0
	v_exp_f32_e32 v26, v0
	v_sub_f32_e32 v0, v45, v49
	v_exp_f32_e32 v44, v22
	v_mul_f32_e32 v22, 0x3fb8aa3b, v0
	v_mul_f32_e32 v0, 0xbfb8aa3b, v0
	v_exp_f32_e32 v45, v22
	v_lshlrev_b32_e32 v48, 16, v27
	v_and_b32_e32 v49, 0xffff0000, v27
	v_exp_f32_e32 v27, v0
	v_pk_mul_f32 v[48:49], v[48:49], s[4:5] op_sel_hi:[1,0]
	v_lshlrev_b32_e32 v22, 16, v23
	v_and_b32_e32 v23, 0xffff0000, v23
	s_waitcnt lgkmcnt(0)
	v_sub_f32_e32 v0, v66, v70
	v_pk_mul_f32 v[44:45], v[48:49], v[44:45]
	v_pk_mul_f32 v[48:49], v[26:27], v[22:23]
	v_mul_f32_e32 v22, 0x3fb8aa3b, v0
	v_mul_f32_e32 v0, 0xbfb8aa3b, v0
	v_exp_f32_e32 v26, v0
	v_sub_f32_e32 v0, v67, v71
	v_mul_f32_e32 v23, 0x3fb8aa3b, v0
	v_exp_f32_e32 v22, v22
	v_exp_f32_e32 v23, v23
	v_mul_f32_e32 v0, 0xbfb8aa3b, v0
	v_exp_f32_e32 v27, v0
	v_lshlrev_b32_e32 v66, 16, v28
	v_and_b32_e32 v67, 0xffff0000, v28
	v_pk_mul_f32 v[66:67], v[66:67], s[4:5] op_sel_hi:[1,0]
	v_sub_f32_e32 v0, v68, v72
	v_pk_mul_f32 v[66:67], v[66:67], v[22:23]
	v_lshlrev_b32_e32 v22, 16, v24
	v_and_b32_e32 v23, 0xffff0000, v24
	v_pk_mul_f32 v[70:71], v[26:27], v[22:23]
	v_mul_f32_e32 v22, 0x3fb8aa3b, v0
	v_mul_f32_e32 v0, 0xbfb8aa3b, v0
	v_exp_f32_e32 v26, v0
	v_sub_f32_e32 v0, v69, v73
	v_mul_f32_e32 v23, 0x3fb8aa3b, v0
	v_exp_f32_e32 v22, v22
	v_exp_f32_e32 v23, v23
	v_mul_f32_e32 v0, 0xbfb8aa3b, v0
	v_exp_f32_e32 v27, v0
	v_lshlrev_b32_e32 v28, 16, v29
	v_and_b32_e32 v29, 0xffff0000, v29
	v_pk_mul_f32 v[28:29], v[28:29], s[4:5] op_sel_hi:[1,0]
	v_exp_f32_e32 v58, v58
	v_pk_mul_f32 v[28:29], v[28:29], v[22:23]
	v_lshlrev_b32_e32 v22, 16, v25
	v_and_b32_e32 v23, 0xffff0000, v25
	v_pk_mul_f32 v[68:69], v[26:27], v[22:23]
	v_cvt_pk_bf16_f32 v22, v42, v43
	v_mul_lo_u32 v42, v64, s17
	v_exp_f32_e32 v59, v59
	v_cvt_pk_bf16_f32 v23, v44, v45
	v_cvt_pk_bf16_f32 v24, v66, v67
	v_cvt_pk_bf16_f32 v25, v28, v29
	v_add_u32_e32 v0, v85, v42
	v_pk_mul_f32 v[46:47], v[46:47], v[74:75]
	ds_write_b128 v0, v[22:25]
	v_lshlrev_b32_e32 v22, 16, v38
	v_and_b32_e32 v23, 0xffff0000, v38
	v_lshlrev_b32_e32 v24, 16, v39
	v_and_b32_e32 v25, 0xffff0000, v39
	v_cvt_pk_bf16_f32 v26, v46, v47
	v_cvt_pk_bf16_f32 v27, v48, v49
	v_cvt_pk_bf16_f32 v28, v70, v71
	v_cvt_pk_bf16_f32 v29, v68, v69
	v_add_u32_e32 v0, v87, v42
	v_pk_mul_f32 v[22:23], v[56:57], v[22:23]
	v_pk_mul_f32 v[24:25], v[54:55], v[24:25]
	ds_write_b128 v0, v[26:29]
	v_cvt_pk_bf16_f32 v22, v22, v23
	v_cvt_pk_bf16_f32 v23, v24, v25
	v_lshlrev_b32_e32 v24, 16, v40
	v_and_b32_e32 v25, 0xffff0000, v40
	v_lshlrev_b32_e32 v26, 16, v41
	v_and_b32_e32 v27, 0xffff0000, v41
	v_add_u32_e32 v0, 0, v50
	v_pk_mul_f32 v[24:25], v[52:53], v[24:25]
	v_pk_mul_f32 v[26:27], v[58:59], v[26:27]
	v_cvt_pk_bf16_f32 v24, v24, v25
	v_cvt_pk_bf16_f32 v25, v26, v27
	v_add_u32_e32 v26, v0, v65
	s_waitcnt lgkmcnt(0)
	s_barrier
; __device__ __forceinline__ unsigned pk2(float lo, float hi) { const f32v2_t v = {lo, hi}; return __builtin_bit_cast(unsigned, __builtin_convertvector(v, bf16v2_t)); }
; __device__ __forceinline__ float bflo(unsigned u) { return __uint_as_float(u << 16); }
; __device__ __forceinline__ float bfhi(unsigned u) { return __uint_as_float(u & 0xffff0000u); }
; __device__ __forceinline__ f32x4 mfma16(bf16x8 a, bf16x8 b, f32x4 c) { return __builtin_amdgcn_mfma_f32_16x16x32_bf16(a, b, c, 0, 0, 0); }
; __device__ __forceinline__ void gla3_item(const Params& p, int item, int l, unsigned char* lds) {
;     ...
; #pragma unroll
;     for (int i = 0; i < 8; ++i) {
;         const int idx = tid + 512 * i, e = idx >> 4, ch = idx & 15;
;         u32x4 o = {pk2(bflo(sv[i][0]) * f31[0], bfhi(sv[i][0]) * f31[1]), pk2(bflo(sv[i][1]) * f31[2], bfhi(sv[i][1]) * f31[3]),
;                    pk2(bflo(sv[i][2]) * f31[4], bfhi(sv[i][2]) * f31[5]), pk2(bflo(sv[i][3]) * f31[6], bfhi(sv[i][3]) * f31[7])};
;         *(u32x4*)(ST + e * 136 + ch * 8) = o;
;     }
;     __syncthreads();
;     const int ib = w & 3, eh = w >> 2, iq = 16 * ib + fr;
;     bf16x8 qf[4];
; #pragma unroll
;     for (int ks = 0; ks < 4; ++ks) qf[ks] = *(const bf16x8*)(Qp + iq * 136 + 32 * ks + 8 * fq);
;     float wgt[4][4];
; #pragma unroll
;     for (int jb = 0; jb < 4; ++jb) {
;         f32x4 s = {0.f, 0.f, 0.f, 0.f};
;         if (jb <= ib) {
; #pragma unroll
;             for (int ks = 0; ks < 4; ++ks) s = mfma16(*(const bf16x8*)(Kp + (16 * jb + fr) * 136 + 32 * ks + 8 * fq), qf[ks], s);
;         }
	ds_write_b128 v26, v[22:25]
	v_lshlrev_b32_e32 v22, 16, v34
	v_and_b32_e32 v23, 0xffff0000, v34
	v_lshlrev_b32_e32 v24, 16, v35
	v_and_b32_e32 v25, 0xffff0000, v35
	v_pk_mul_f32 v[22:23], v[56:57], v[22:23]
	v_pk_mul_f32 v[24:25], v[54:55], v[24:25]
	v_cvt_pk_bf16_f32 v22, v22, v23
	v_cvt_pk_bf16_f32 v23, v24, v25
	v_lshlrev_b32_e32 v24, 16, v36
	v_and_b32_e32 v25, 0xffff0000, v36
	v_lshlrev_b32_e32 v26, 16, v37
	v_and_b32_e32 v27, 0xffff0000, v37
	v_pk_mul_f32 v[24:25], v[52:53], v[24:25]
	v_pk_mul_f32 v[26:27], v[58:59], v[26:27]
	v_cvt_pk_bf16_f32 v24, v24, v25
	v_cvt_pk_bf16_f32 v25, v26, v27
	v_add_u32_e32 v26, v0, v42
	ds_write_b128 v26, v[22:25]
	v_lshlrev_b32_e32 v22, 16, v30
	v_and_b32_e32 v23, 0xffff0000, v30
	v_lshlrev_b32_e32 v24, 16, v31
	v_and_b32_e32 v25, 0xffff0000, v31
	v_pk_mul_f32 v[22:23], v[56:57], v[22:23]
	v_pk_mul_f32 v[24:25], v[54:55], v[24:25]
	v_cvt_pk_bf16_f32 v22, v22, v23
	v_cvt_pk_bf16_f32 v23, v24, v25
	v_lshlrev_b32_e32 v24, 16, v32
	v_and_b32_e32 v25, 0xffff0000, v32
	v_lshlrev_b32_e32 v26, 16, v33
	v_and_b32_e32 v27, 0xffff0000, v33
	v_lshrrev_b32_e32 v28, 4, v63
	v_pk_mul_f32 v[24:25], v[52:53], v[24:25]
	v_pk_mul_f32 v[26:27], v[58:59], v[26:27]
	v_cvt_pk_bf16_f32 v24, v24, v25
	v_cvt_pk_bf16_f32 v25, v26, v27
	v_mad_u64_u32 v[26:27], s[4:5], v28, s17, v[0:1]
	ds_write_b128 v26, v[22:25]
	v_lshlrev_b32_e32 v22, 16, v18
	v_and_b32_e32 v23, 0xffff0000, v18
	v_pk_mul_f32 v[22:23], v[56:57], v[22:23]
	v_lshrrev_b32_e32 v24, 4, v62
	v_cvt_pk_bf16_f32 v18, v22, v23
	v_lshlrev_b32_e32 v22, 16, v19
	v_and_b32_e32 v23, 0xffff0000, v19
	v_pk_mul_f32 v[22:23], v[54:55], v[22:23]
	s_nop 0
	v_cvt_pk_bf16_f32 v19, v22, v23
	v_lshlrev_b32_e32 v22, 16, v20
	v_and_b32_e32 v23, 0xffff0000, v20
	v_pk_mul_f32 v[22:23], v[52:53], v[22:23]
	s_nop 0
	v_cvt_pk_bf16_f32 v20, v22, v23
	v_lshlrev_b32_e32 v22, 16, v21
	v_and_b32_e32 v23, 0xffff0000, v21
	v_pk_mul_f32 v[22:23], v[58:59], v[22:23]
	s_nop 0
	v_cvt_pk_bf16_f32 v21, v22, v23
	v_mad_u64_u32 v[22:23], s[4:5], v24, s17, v[0:1]
	ds_write_b128 v22, v[18:21]
	v_add_u32_e32 v18, 0x800, v60
	v_lshrrev_b32_e32 v20, 4, v18
	v_lshlrev_b32_e32 v18, 16, v14
	v_and_b32_e32 v19, 0xffff0000, v14
	v_pk_mul_f32 v[18:19], v[56:57], v[18:19]
	s_nop 0
	v_cvt_pk_bf16_f32 v14, v18, v19
	v_lshlrev_b32_e32 v18, 16, v15
	v_and_b32_e32 v19, 0xffff0000, v15
	v_pk_mul_f32 v[18:19], v[54:55], v[18:19]
	s_nop 0
	v_cvt_pk_bf16_f32 v15, v18, v19
	v_lshlrev_b32_e32 v18, 16, v16
	v_and_b32_e32 v19, 0xffff0000, v16
	v_pk_mul_f32 v[18:19], v[52:53], v[18:19]
	s_nop 0
	v_cvt_pk_bf16_f32 v16, v18, v19
	v_lshlrev_b32_e32 v18, 16, v17
	v_and_b32_e32 v19, 0xffff0000, v17
	v_pk_mul_f32 v[18:19], v[58:59], v[18:19]
	s_nop 0
	v_cvt_pk_bf16_f32 v17, v18, v19
	v_mad_u64_u32 v[18:19], s[4:5], v20, s17, v[0:1]
	ds_write_b128 v18, v[14:17]
	v_add_u32_e32 v14, 0xa00, v60
	v_lshrrev_b32_e32 v16, 4, v14
	v_lshlrev_b32_e32 v14, 16, v10
	v_and_b32_e32 v15, 0xffff0000, v10
	v_pk_mul_f32 v[14:15], v[56:57], v[14:15]
	s_nop 0
	v_cvt_pk_bf16_f32 v10, v14, v15
	v_lshlrev_b32_e32 v14, 16, v11
	v_and_b32_e32 v15, 0xffff0000, v11
	v_pk_mul_f32 v[14:15], v[54:55], v[14:15]
	s_nop 0
	v_cvt_pk_bf16_f32 v11, v14, v15
	v_lshlrev_b32_e32 v14, 16, v12
	v_and_b32_e32 v15, 0xffff0000, v12
	v_pk_mul_f32 v[14:15], v[52:53], v[14:15]
	s_nop 0
	v_cvt_pk_bf16_f32 v12, v14, v15
	v_lshlrev_b32_e32 v14, 16, v13
	v_and_b32_e32 v15, 0xffff0000, v13
	v_pk_mul_f32 v[14:15], v[58:59], v[14:15]
	s_nop 0
	v_cvt_pk_bf16_f32 v13, v14, v15
	v_mad_u64_u32 v[14:15], s[4:5], v16, s17, v[0:1]
	ds_write_b128 v14, v[10:13]
	v_add_u32_e32 v10, 0xc00, v60
	v_lshrrev_b32_e32 v12, 4, v10
	v_lshlrev_b32_e32 v10, 16, v6
	v_and_b32_e32 v11, 0xffff0000, v6
	v_pk_mul_f32 v[10:11], v[56:57], v[10:11]
	s_nop 0
	v_cvt_pk_bf16_f32 v6, v10, v11
	v_lshlrev_b32_e32 v10, 16, v7
	v_and_b32_e32 v11, 0xffff0000, v7
	v_pk_mul_f32 v[10:11], v[54:55], v[10:11]
	s_nop 0
	v_cvt_pk_bf16_f32 v7, v10, v11
	v_lshlrev_b32_e32 v10, 16, v8
	v_and_b32_e32 v11, 0xffff0000, v8
	v_pk_mul_f32 v[10:11], v[52:53], v[10:11]
	s_nop 0
	v_cvt_pk_bf16_f32 v8, v10, v11
	v_lshlrev_b32_e32 v10, 16, v9
	v_and_b32_e32 v11, 0xffff0000, v9
	v_pk_mul_f32 v[10:11], v[58:59], v[10:11]
	s_nop 0
	v_cvt_pk_bf16_f32 v9, v10, v11
	v_mad_u64_u32 v[10:11], s[4:5], v12, s17, v[0:1]
	ds_write_b128 v10, v[6:9]
	v_add_u32_e32 v6, 0xe00, v60
	v_lshrrev_b32_e32 v8, 4, v6
	v_lshlrev_b32_e32 v6, 16, v2
	v_and_b32_e32 v7, 0xffff0000, v2
	v_pk_mul_f32 v[6:7], v[56:57], v[6:7]
	s_nop 0
	v_cvt_pk_bf16_f32 v2, v6, v7
	v_lshlrev_b32_e32 v6, 16, v3
	v_and_b32_e32 v7, 0xffff0000, v3
	v_pk_mul_f32 v[6:7], v[54:55], v[6:7]
	s_nop 0
	v_cvt_pk_bf16_f32 v3, v6, v7
	v_lshlrev_b32_e32 v6, 16, v4
	v_and_b32_e32 v7, 0xffff0000, v4
	v_pk_mul_f32 v[6:7], v[52:53], v[6:7]
	s_nop 0
	v_cvt_pk_bf16_f32 v4, v6, v7
	v_lshlrev_b32_e32 v6, 16, v5
	v_and_b32_e32 v7, 0xffff0000, v5
	v_pk_mul_f32 v[6:7], v[58:59], v[6:7]
	s_nop 0
	v_cvt_pk_bf16_f32 v5, v6, v7
	v_mad_u64_u32 v[6:7], s[4:5], v8, s17, v[0:1]
	v_and_b32_e32 v0, 48, v60
	v_add_u32_e32 v20, s16, v0
	ds_write_b128 v6, v[2:5]
	v_mad_u32_u24 v6, v61, s17, v20
	s_waitcnt lgkmcnt(0)
	s_barrier
	ds_read_b128 v[2:5], v6
	v_bfe_u32 v7, v60, 6, 2
	v_lshl_or_b32 v54, v7, 4, v61
	v_mul_u32_u24_e32 v8, 0x110, v54
	v_add3_u32 v21, s15, v8, v0
	ds_read_b128 v[8:11], v6 offset:64
	ds_read_b128 v[26:29], v21
	ds_read_b128 v[22:25], v21 offset:64
	ds_read_b128 v[12:15], v6 offset:128
	s_waitcnt lgkmcnt(2)
	v_mfma_f32_16x16x32_bf16 v[2:5], v[2:5], v[26:29], 0
	s_movk_i32 s16, 0x110
	v_cmp_ne_u32_e32 vcc, 0, v7
	s_waitcnt lgkmcnt(1)
	v_mfma_f32_16x16x32_bf16 v[8:11], v[8:11], v[22:25], v[2:5]
	ds_read_b128 v[16:19], v6 offset:192
	ds_read_b128 v[30:33], v21 offset:128
	s_nop 1
	ds_read_b128 v[2:5], v21 offset:192
	v_mov_b32_e32 v6, 0
	s_waitcnt lgkmcnt(1)
	v_mfma_f32_16x16x32_bf16 v[8:11], v[12:15], v[30:33], v[8:11]
	v_mul_u32_u24_e32 v14, 0x110, v61
	v_add_u32_e32 v34, v20, v14
	v_mov_b32_e32 v14, 0
	s_waitcnt lgkmcnt(0)
	v_mfma_f32_16x16x32_bf16 v[10:13], v[16:19], v[2:5], v[8:11]
	v_mov_b32_e32 v15, 0
	v_mov_b32_e32 v16, 0
	v_mov_b32_e32 v17, 0
	s_and_saveexec_b64 s[42:43], vcc
	v_readlane_b32 s15, v247, 36
	s_cbranch_execz .LBB0_62
	ds_read_b128 v[14:17], v34 offset:4352
	ds_read_b128 v[18:21], v34 offset:4416
	s_waitcnt lgkmcnt(1)
	v_mfma_f32_16x16x32_bf16 v[14:17], v[14:17], v[26:29], 0
	s_waitcnt lgkmcnt(0)
	v_mfma_f32_16x16x32_bf16 v[14:17], v[18:21], v[22:25], v[14:17]
	ds_read_b128 v[18:21], v34 offset:4480
	s_waitcnt lgkmcnt(0)
	v_mfma_f32_16x16x32_bf16 v[14:17], v[18:21], v[30:33], v[14:17]
	ds_read_b128 v[18:21], v34 offset:4544
	s_waitcnt lgkmcnt(0)
	v_mfma_f32_16x16x32_bf16 v[14:17], v[18:21], v[2:5], v[14:17]
